# strategy 4a on the GEMM phases, other half: flips deleted, one static s_setprio 1 for waves 0-3 set at each tile-loop header
# baseline (speedup 1.0000x reference)
; template <class Epi, class Sched, bool ALIGN_EPI = false, bool SP2 = false>
; __device__ __forceinline__ void gemm_phase(PG8_LAS unsigned char* lds, const Gemm g, const Sched& S, const Epi& E) {
;     ...
;     for (;;) {
;         const bool has_next = S.next(ui + 1, nxt);
;         const char* nA = has_next ? (const char*)g.A + (size_t)nxt.pm * tstep : cA; const char* nB = has_next ? (const char*)g.Bt + (size_t)nxt.pn * tstep : cB;
;         for (int t = 0; t < nt; t += 2) {
.LBB0_65:
	v_cmp_gt_u32_e32 vcc, 0x100, v178
	s_cbranch_vccz .Lgprio_skip0
	s_setprio 1
